# v60 + phase-0 rebalance: WGs 0..127 run the SSM-table job (30 us serial) + one tail job, WGs 128..255 walk the other 832 jobs with stride 128
# speedup vs baseline: 1.0143x; 1.0143x over previous
.LBB0_19:
	s_cmp_lt_i32 s26, 1
	s_cselect_b64 s[10:11], -1, 0
	s_cmp_gt_i32 s27, 0
	s_cselect_b64 s[0:1], -1, 0
	s_cmpk_lt_i32 s96, 0x440
	s_cselect_b64 s[4:5], -1, 0
	s_and_b64 s[4:5], s[4:5], s[10:11]
	s_and_b64 s[0:1], s[4:5], s[0:1]
	v_writelane_b32 v254, s96, 37
	s_mov_b32 s13, 0
	s_andn2_b64 vcc, exec, s[0:1]
	v_and_b32_e32 v228, 15, v0
	v_writelane_b32 v254, s26, 38
	s_nop 1
	v_writelane_b32 v254, s27, 39
	s_cbranch_vccnz .LBB0_103
	v_and_b32_e32 v1, 0x3ff, v0
	v_lshlrev_b32_e32 v8, 3, v1
	v_and_b32_e32 v4, 0xf8, v8
	v_mul_u32_u24_e32 v6, 0x41, v4
	v_bfe_u32 v89, v0, 5, 5
	v_lshlrev_b32_e32 v6, 2, v6
	s_add_u32 s0, s78, 0x600000
	v_lshlrev_b32_e32 v7, 2, v89
	v_add_u32_e32 v9, 0, v6
	s_addc_u32 s1, s79, 0
	v_add3_u32 v90, 0, v7, v6
	v_add_u32_e32 v91, v9, v7
	v_or_b32_e32 v7, 0x200, v1
	v_bfe_u32 v2, v0, 4, 6
	v_mov_b32_e32 v3, 0xffff9800
	s_add_u32 s92, s78, 0x580000
	v_lshrrev_b32_e32 v92, 5, v7
	v_and_or_b32 v86, v2, 28, v3
	v_lshlrev_b32_e32 v3, 2, v1
	s_addc_u32 s93, s79, 0
	s_movk_i32 s2, 0xf8
	v_lshlrev_b32_e32 v7, 2, v92
	v_and_b32_e32 v5, 0xfc, v3
	s_add_u32 s94, s78, 0x380000
	v_add3_u32 v93, 0, v7, v6
	v_add_u32_e32 v94, v9, v7
	v_or_b32_e32 v7, 0x600, v1
	v_bitop3_b32 v3, v3, s2, v3 bitop3:0xc
	s_addc_u32 s95, s79, 0
	v_lshrrev_b32_e32 v96, 5, v7
	v_add_u32_e32 v101, 0, v3
	v_lshlrev_b32_e32 v3, 6, v1
	v_readlane_b32 s16, v254, 5
	s_mov_b32 s90, s96
	s_add_u32 s96, s78, 0x180000
	v_lshlrev_b32_e32 v7, 2, v96
	v_and_b32_e32 v3, 64, v3
	v_lshlrev_b32_e32 v66, 2, v5
	v_mov_b32_e32 v67, 0
	v_readlane_b32 s17, v254, 6
	v_readlane_b32 s20, v254, 9
	v_readlane_b32 s21, v254, 10
	s_addc_u32 s97, s79, 0
	v_add_u32_e32 v98, v9, v7
	v_mul_u32_u24_e32 v9, 0x78, v1
	v_add_u32_e32 v102, 0, v3
	v_lshlrev_b32_e32 v3, 4, v1
	v_lshl_add_u64 v[68:69], s[16:17], 0, v[66:67]
	v_lshl_add_u64 v[70:71], s[20:21], 0, v[66:67]
	s_add_u32 s14, s78, 0x80000
	v_mul_u32_u24_e32 v11, 0x88, v1
	v_bfe_u32 v100, v1, 4, 2
	v_and_b32_e32 v66, 0x3f0, v3
	v_add3_u32 v3, v9, v8, 0
	s_movk_i32 s2, 0x4200
	s_addc_u32 s15, s79, 0
	v_add_u32_e32 v103, 0x200, v3
	v_add3_u32 v104, v3, v11, s2
	v_lshl_add_u32 v3, v100, 9, 0
	s_add_u32 s80, s78, 0x800000
	v_bfe_u32 v87, v0, 6, 4
	v_add_u32_e32 v107, 0x2200, v3
	v_lshl_add_u32 v3, v228, 3, 0
	s_addc_u32 s81, s79, 0
	v_add_u32_e32 v108, 0x200, v3
	v_lshl_add_u32 v3, v87, 3, 0
	s_add_u32 s34, s78, 0x1600000
	v_add_u32_e32 v109, 0x4200, v3
	v_mbcnt_lo_u32_b32 v3, -1, 0
	s_addc_u32 s35, s79, 0
	v_add_u32_e32 v99, 0, v8
	s_movk_i32 s4, 0x78
	v_mbcnt_hi_u32_b32 v110, -1, v3
	v_readlane_b32 s18, v254, 7
	v_readlane_b32 s19, v254, 8
	v_readlane_b32 s22, v254, 11
	v_readlane_b32 s23, v254, 12
	v_readlane_b32 s24, v254, 13
	v_readlane_b32 s25, v254, 14
	v_readlane_b32 s26, v254, 15
	v_readlane_b32 s27, v254, 16
	v_readlane_b32 s28, v254, 17
	v_readlane_b32 s29, v254, 18
	v_readlane_b32 s30, v254, 19
	v_readlane_b32 s31, v254, 20
	v_writelane_b32 v254, s0, 40
	v_and_b32_e32 v2, 63, v0
	v_add3_u32 v97, 0, v7, v6
	s_add_u32 s52, s78, 0xe800000
	v_mad_u32_u24 v10, v1, s4, v99
	v_lshl_add_u64 v[6:7], s[78:79], 0, v[66:67]
	s_mov_b64 s[4:5], 0x2a00000
	v_lshlrev_b32_e32 v66, 1, v5
	v_and_b32_e32 v3, 64, v110
	v_writelane_b32 v254, s1, 41
	v_lshl_add_u32 v88, v2, 2, 0
	v_or_b32_e32 v95, 32, v89
	s_addc_u32 s53, s79, 0
	v_cmp_gt_u32_e64 s[0:1], 64, v1
	v_lshl_add_u64 v[72:73], v[6:7], 0, s[4:5]
	v_lshl_add_u64 v[74:75], s[76:77], 0, v[66:67]
	v_add_u32_e32 v105, 0x2200, v99
	v_or_b32_e32 v106, 0xfffffe00, v1
	v_add_u32_e32 v111, 64, v3
	v_xor_b32_e32 v112, 32, v110
	v_xor_b32_e32 v113, 16, v110
	s_mov_b32 s54, 0x3a800000
	s_mov_b32 s2, 0x800000
	v_lshlrev_b32_e32 v76, 2, v2
	v_lshlrev_b32_e32 v78, 1, v4
	s_mov_b32 s91, 0x3fb8aa3b
	s_mov_b32 s82, 0xc2ce8ed0
	s_mov_b32 s55, 0x42b17218
	s_mov_b32 s83, 0xdb629599
	s_mov_b32 s84, 0xf534ddc0
	s_mov_b32 s85, 0xfc2757d1
	s_mov_b32 s86, 0x4e441529
	s_mov_b32 s87, 0xa2f9836e
	s_mov_b32 s88, 0x3fc90fda
	s_mov_b32 s89, 0xbfc90fda
	v_mov_b32_e32 v114, 0x3c0881c4
	v_mov_b32_e32 v115, 0xbab64f3b
	v_add_u32_e32 v116, v10, v11
	v_xor_b32_e32 v117, 8, v110
	v_mov_b32_e32 v118, 0x7f800000
	v_not_b32_e32 v119, 63
	v_not_b32_e32 v120, 31
	v_mov_b32_e32 v121, 0x7fc00000
	s_mov_b64 s[56:57], 0x800
	s_mov_b32 s98, s3
	s_movk_i32 s99, 0x440
	s_cmpk_lg_u32 s3, 0x100
	s_cbranch_scc1 .Lp0_bal_done
	s_movk_i32 s98, 0x3c0
	s_cmpk_lt_u32 s90, 0x80
	s_cbranch_scc1 .Lp0_bal_done
	s_movk_i32 s98, 0x80
	s_movk_i32 s99, 0x3c0

.LBB0_21:
	s_add_i32 s90, s90, s98
	s_cmp_lt_i32 s90, s99
	s_cbranch_scc0 .LBB0_102
